# P0 weight conversion loop rewritten by hand: two 64x64 items in flight per wave, gains loaded up front, LDS reads batched before one wait
# baseline (speedup 1.0000x reference)
.LBB0_11:
	s_or_b64 exec, exec, s[4:5]
	s_lshr_b32 s3, s74, 6
	s_lshl_b32 s4, s2, 3
	v_writelane_b32 v254, s4, 6
	s_add_i32 s70, s3, s4
	s_lshl_b32 s4, s44, 3
	v_and_b32_e32 v1, 63, v1
	v_writelane_b32 v254, s4, 7
	s_cmp_gt_i32 s70, 0xbbff
	v_lshlrev_b32_e32 v66, 2, v1
	v_writelane_b32 v254, s5, 8
	s_cbranch_scc1 .LBB0_76
	s_waitcnt lgkmcnt(0)
	v_lshrrev_b32_e32 v85, 4, v1
	v_and_b32_e32 v86, 15, v1
	v_lshlrev_b32_e32 v86, 4, v86
	v_lshlrev_b32_e32 v87, 2, v85
	s_mul_i32 s4, s3, 0x4100
	v_mul_u32_u24_e32 v88, 0x104, v85
	v_add_u32_e32 v88, v88, v86
	v_add_u32_e32 v88, s4, v88
	v_and_b32_e32 v91, 7, v1
	v_lshrrev_b32_e32 v90, 3, v1
	v_mul_u32_u24_e32 v89, 0x820, v91
	v_lshl_add_u32 v89, v90, 2, v89
	v_add_u32_e32 v89, s4, v89
	v_lshlrev_b32_e32 v91, 4, v91
	s_mov_b32 s58, s70
	v_readlane_b32 s59, v254, 7
	s_mov_b32 s4, s58
	s_cmpk_lt_u32 s4, 0x1000
	s_cbranch_scc1 .Lp0_c0_2
	s_sub_u32 s4, s4, 0x1000
	s_cmpk_lt_u32 s4, 0x800
	s_cbranch_scc1 .Lp0_c1_3
	s_sub_u32 s4, s4, 0x800
	s_cmpk_lt_u32 s4, 0x800
	s_cbranch_scc1 .Lp0_c2_4
	s_sub_u32 s4, s4, 0x800
	s_cmpk_lt_u32 s4, 0x1000
	s_cbranch_scc1 .Lp0_c3_5
	s_sub_u32 s4, s4, 0x1000
	s_cmpk_lt_u32 s4, 0x800
	s_cbranch_scc1 .Lp0_c4_6
	s_sub_u32 s4, s4, 0x800
	s_cmpk_lt_u32 s4, 0x5800
	s_cbranch_scc1 .Lp0_c5_7
	s_sub_u32 s4, s4, 0x5800
	s_branch .Lp0_c6_8
.Lp0_c0_2:
	s_lshr_b32 s5, s4, 11
	s_and_b32 s6, s4, 0x7ff
	s_lshr_b32 s7, s6, 6
	s_and_b32 s8, s6, 63
	s_lshl_b32 s7, s7, 6
	s_lshl_b32 s8, s8, 6
	s_mov_b32 s9, s8
	s_mul_i32 s10, s7, 0x4000
	s_lshl_b32 s11, s8, 2
	s_add_u32 s10, s10, s11
	s_mul_i32 s11, s5, 0x2000000
	s_add_u32 s10, s10, s11
	s_add_u32 s14, s50, s10
	s_addc_u32 s15, s51, 0
	s_lshl_b32 s10, s5, 13
	s_lshl_b32 s11, s7, 2
	s_add_u32 s10, s10, s11
	s_add_u32 s16, s22, s10
	s_addc_u32 s17, s23, 0
	s_mov_b32 s41, 1
	s_mul_i32 s10, s9, 0x1000
	s_lshl_b32 s11, s7, 1
	s_add_u32 s10, s10, s11
	s_mul_i32 s11, s5, 0x1000000
	s_add_u32 s10, s10, s11
	s_add_u32 s10, s10, 0x600000
	s_add_u32 s18, s48, s10
	s_addc_u32 s19, s49, 0
	s_mov_b32 s33, 0x4000
	s_mov_b32 s40, 0x1000
	s_branch .Lp0_dec_done_1
.Lp0_c1_3:
	s_lshr_b32 s5, s4, 10
	s_and_b32 s6, s4, 0x3ff
	s_lshr_b32 s7, s6, 5
	s_and_b32 s8, s6, 31
	s_lshl_b32 s7, s7, 6
	s_lshl_b32 s8, s8, 6
	s_mov_b32 s9, s8
	s_mul_i32 s10, s7, 0x2000
	s_lshl_b32 s11, s8, 2
	s_add_u32 s10, s10, s11
	s_mul_i32 s11, s5, 0x1000000
	s_add_u32 s10, s10, s11
	s_add_u32 s14, s24, s10
	s_addc_u32 s15, s25, 0
	s_mov_b64 s[16:17], s[22:23]
	s_mov_b32 s41, 0
	s_mul_i32 s10, s9, 0x1000
	s_lshl_b32 s11, s7, 1
	s_add_u32 s10, s10, s11
	s_mul_i32 s11, s5, 0x800000
	s_add_u32 s10, s10, s11
	s_add_u32 s10, s10, 0x2600000
	s_add_u32 s18, s48, s10
	s_addc_u32 s19, s49, 0
	s_mov_b32 s33, 0x2000
	s_mov_b32 s40, 0x1000
	s_branch .Lp0_dec_done_1
.Lp0_c2_4:
	s_mov_b32 s5, 0
	s_mov_b32 s6, s4
	s_lshr_b32 s7, s6, 6
	s_and_b32 s8, s6, 63
	s_lshl_b32 s7, s7, 6
	s_lshl_b32 s8, s8, 6
	s_mov_b32 s9, s8
	s_mul_i32 s10, s7, 0x4040
	s_lshl_b32 s11, s8, 2
	s_add_u32 s10, s10, s11
	s_add_u32 s14, s52, s10
	s_addc_u32 s15, s53, 0
	s_lshl_b32 s10, s5, 13
	s_lshl_b32 s11, s7, 2
	s_add_u32 s10, s10, s11
	s_add_u32 s16, s26, s10
	s_addc_u32 s17, s27, 0
	s_mov_b32 s41, 1
	s_mul_i32 s10, s9, 0x1000
	s_lshl_b32 s11, s7, 1
	s_add_u32 s10, s10, s11
	s_add_u32 s10, s10, 0x3600000
	s_add_u32 s18, s48, s10
	s_addc_u32 s19, s49, 0
	s_mov_b32 s33, 0x4040
	s_mov_b32 s40, 0x1000
	s_branch .Lp0_dec_done_1
.Lp0_c3_5:
	s_lshr_b32 s5, s4, 11
	s_and_b32 s6, s4, 0x7ff
	s_lshr_b32 s7, s6, 6
	s_and_b32 s8, s6, 63
	s_lshl_b32 s7, s7, 6
	s_lshl_b32 s8, s8, 6
	s_mov_b32 s9, s8
	s_mul_i32 s10, s7, 0x4000
	s_lshl_b32 s11, s8, 2
	s_add_u32 s10, s10, s11
	s_mul_i32 s11, s5, 0x2000000
	s_add_u32 s10, s10, s11
	s_add_u32 s14, s30, s10
	s_addc_u32 s15, s31, 0
	s_lshl_b32 s10, s5, 13
	s_lshl_b32 s11, s7, 2
	s_add_u32 s10, s10, s11
	s_add_u32 s16, s28, s10
	s_addc_u32 s17, s29, 0
	s_mov_b32 s41, 1
	s_mul_i32 s10, s9, 0x1000
	s_lshl_b32 s11, s7, 1
	s_add_u32 s10, s10, s11
	s_mul_i32 s11, s5, 0x1000000
	s_add_u32 s10, s10, s11
	s_add_u32 s10, s10, 0x4600000
	s_add_u32 s18, s48, s10
	s_addc_u32 s19, s49, 0
	s_mov_b32 s33, 0x4000
	s_mov_b32 s40, 0x1000
	s_branch .Lp0_dec_done_1
.Lp0_c4_6:
	s_lshr_b32 s5, s4, 10
	s_and_b32 s6, s4, 0x3ff
	s_lshr_b32 s7, s6, 5
	s_and_b32 s8, s6, 31
	s_lshl_b32 s7, s7, 6
	s_lshl_b32 s8, s8, 6
	s_mov_b32 s9, s8
	s_mul_i32 s10, s7, 0x2000
	s_lshl_b32 s11, s8, 2
	s_add_u32 s10, s10, s11
	s_mul_i32 s11, s5, 0x1000000
	s_add_u32 s10, s10, s11
	s_add_u32 s14, s36, s10
	s_addc_u32 s15, s37, 0
	s_mov_b64 s[16:17], s[22:23]
	s_mov_b32 s41, 0
	s_mul_i32 s10, s9, 0x1000
	s_lshl_b32 s11, s7, 1
	s_add_u32 s10, s10, s11
	s_mul_i32 s11, s5, 0x800000
	s_add_u32 s10, s10, s11
	s_add_u32 s10, s10, 0x6600000
	s_add_u32 s18, s48, s10
	s_addc_u32 s19, s49, 0
	s_mov_b32 s33, 0x2000
	s_mov_b32 s40, 0x1000
	s_branch .Lp0_dec_done_1
.Lp0_c5_7:
	s_lshr_b32 s5, s4, 5
	s_mul_i32 s5, s5, 0x1746
	s_lshr_b32 s5, s5, 20
	s_mul_i32 s6, s5, 0x1600
	s_sub_u32 s6, s4, s6
	s_mul_i32 s7, s6, 0x1746
	s_lshr_b32 s7, s7, 20
	s_mul_i32 s8, s7, 0xb0
	s_sub_u32 s8, s6, s8
	s_lshl_b32 s7, s7, 6
	s_lshl_b32 s8, s8, 6
	s_cmpk_lt_u32 s8, 0x1600
	s_cbranch_scc0 .Lp0_uprow_hi_9
	s_lshr_b32 s9, s8, 7
	s_lshl_b32 s9, s9, 8
	s_and_b32 s10, s8, 0x7f
	s_add_u32 s9, s9, s10
	s_branch .Lp0_uprow_done_10
.Lp0_uprow_hi_9:
	s_sub_u32 s10, s8, 0x1600
	s_lshr_b32 s9, s10, 7
	s_lshl_b32 s9, s9, 8
	s_and_b32 s10, s10, 0x7f
	s_add_u32 s9, s9, s10
	s_add_u32 s9, s9, 0x80
.Lp0_uprow_done_10:
	s_mul_i32 s10, s7, 0xb000
	s_lshl_b32 s11, s8, 2
	s_add_u32 s10, s10, s11
	s_mul_i32 s11, s5, 0x5800000
	s_add_u32 s10, s10, s11
	s_add_u32 s14, s54, s10
	s_addc_u32 s15, s55, 0
	s_lshl_b32 s10, s5, 13
	s_lshl_b32 s11, s7, 2
	s_add_u32 s10, s10, s11
	s_add_u32 s16, s38, s10
	s_addc_u32 s17, s39, 0
	s_mov_b32 s41, 1
	s_mul_i32 s10, s9, 0x1000
	s_lshl_b32 s11, s7, 1
	s_add_u32 s10, s10, s11
	s_mul_i32 s11, s5, 0x2c00000
	s_add_u32 s10, s10, s11
	s_add_u32 s10, s10, 0x7600000
	s_add_u32 s18, s48, s10
	s_addc_u32 s19, s49, 0
	s_mov_b32 s33, 0xb000
	s_mov_b32 s40, 0x1000
	s_branch .Lp0_dec_done_1
.Lp0_c6_8:
	s_lshr_b32 s5, s4, 4
	s_mul_i32 s5, s5, 0x1746
	s_lshr_b32 s5, s5, 20
	s_mul_i32 s6, s5, 0xb00
	s_sub_u32 s6, s4, s6
	s_lshr_b32 s7, s6, 5
	s_and_b32 s8, s6, 31
	s_lshl_b32 s7, s7, 6
	s_lshl_b32 s8, s8, 6
	s_mov_b32 s9, s8
	s_mul_i32 s10, s7, 0x2000
	s_lshl_b32 s11, s8, 2
	s_add_u32 s10, s10, s11
	s_mul_i32 s11, s5, 0x2c00000
	s_add_u32 s10, s10, s11
	s_add_u32 s14, s56, s10
	s_addc_u32 s15, s57, 0
	s_mov_b64 s[16:17], s[22:23]
	s_mov_b32 s41, 0
	s_mul_i32 s10, s9, 0x2c00
	s_lshl_b32 s11, s7, 1
	s_add_u32 s10, s10, s11
	s_mul_i32 s11, s5, 0x1600000
	s_add_u32 s10, s10, s11
	s_add_u32 s10, s10, 0x12600000
	s_add_u32 s18, s48, s10
	s_addc_u32 s19, s49, 0
	s_mov_b32 s33, 0x2000
	s_mov_b32 s40, 0x2c00
.Lp0_dec_done_1:
	v_mad_u32_u24 v172, s33, v85, v86
	v_mad_u32_u24 v173, s40, v90, v91
	s_mov_b64 s[42:43], s[14:15]
	s_lshl_b32 s46, s33, 2
	global_load_dwordx4 v[92:95], v172, s[42:43]
	s_add_u32 s42, s42, s46
	s_addc_u32 s43, s43, 0
	global_load_dwordx4 v[96:99], v172, s[42:43]
	s_add_u32 s42, s42, s46
	s_addc_u32 s43, s43, 0
	global_load_dwordx4 v[100:103], v172, s[42:43]
	s_add_u32 s42, s42, s46
	s_addc_u32 s43, s43, 0
	global_load_dwordx4 v[104:107], v172, s[42:43]
	s_add_u32 s42, s42, s46
	s_addc_u32 s43, s43, 0
	global_load_dwordx4 v[108:111], v172, s[42:43]
	s_add_u32 s42, s42, s46
	s_addc_u32 s43, s43, 0
	global_load_dwordx4 v[112:115], v172, s[42:43]
	s_add_u32 s42, s42, s46
	s_addc_u32 s43, s43, 0
	global_load_dwordx4 v[116:119], v172, s[42:43]
	s_add_u32 s42, s42, s46
	s_addc_u32 s43, s43, 0
	global_load_dwordx4 v[120:123], v172, s[42:43]
	s_add_u32 s42, s42, s46
	s_addc_u32 s43, s43, 0
	global_load_dwordx4 v[124:127], v172, s[42:43]
	s_add_u32 s42, s42, s46
	s_addc_u32 s43, s43, 0
	global_load_dwordx4 v[128:131], v172, s[42:43]
	s_add_u32 s42, s42, s46
	s_addc_u32 s43, s43, 0
	global_load_dwordx4 v[132:135], v172, s[42:43]
	s_add_u32 s42, s42, s46
	s_addc_u32 s43, s43, 0
	global_load_dwordx4 v[136:139], v172, s[42:43]
	s_add_u32 s42, s42, s46
	s_addc_u32 s43, s43, 0
	global_load_dwordx4 v[140:143], v172, s[42:43]
	s_add_u32 s42, s42, s46
	s_addc_u32 s43, s43, 0
	global_load_dwordx4 v[144:147], v172, s[42:43]
	s_add_u32 s42, s42, s46
	s_addc_u32 s43, s43, 0
	global_load_dwordx4 v[148:151], v172, s[42:43]
	s_add_u32 s42, s42, s46
	s_addc_u32 s43, s43, 0
	global_load_dwordx4 v[152:155], v172, s[42:43]
	global_load_dword v156, v87, s[16:17]
	global_load_dword v157, v87, s[16:17] offset:16
	global_load_dword v158, v87, s[16:17] offset:32
	global_load_dword v159, v87, s[16:17] offset:48
	global_load_dword v160, v87, s[16:17] offset:64
	global_load_dword v161, v87, s[16:17] offset:80
	global_load_dword v162, v87, s[16:17] offset:96
	global_load_dword v163, v87, s[16:17] offset:112
	global_load_dword v164, v87, s[16:17] offset:128
	global_load_dword v165, v87, s[16:17] offset:144
	global_load_dword v166, v87, s[16:17] offset:160
	global_load_dword v167, v87, s[16:17] offset:176
	global_load_dword v168, v87, s[16:17] offset:192
	global_load_dword v169, v87, s[16:17] offset:208
	global_load_dword v170, v87, s[16:17] offset:224
	global_load_dword v171, v87, s[16:17] offset:240
.Lp0_top:
	s_add_u32 s58, s58, s59
	s_cmp_gt_u32 s58, 0xbbff
	s_cbranch_scc1 .Lp0_lastA
	s_mov_b32 s4, s58
	s_cmpk_lt_u32 s4, 0x1000
	s_cbranch_scc1 .Lp0_c0_12
	s_sub_u32 s4, s4, 0x1000
	s_cmpk_lt_u32 s4, 0x800
	s_cbranch_scc1 .Lp0_c1_13
	s_sub_u32 s4, s4, 0x800
	s_cmpk_lt_u32 s4, 0x800
	s_cbranch_scc1 .Lp0_c2_14
	s_sub_u32 s4, s4, 0x800
	s_cmpk_lt_u32 s4, 0x1000
	s_cbranch_scc1 .Lp0_c3_15
	s_sub_u32 s4, s4, 0x1000
	s_cmpk_lt_u32 s4, 0x800
	s_cbranch_scc1 .Lp0_c4_16
	s_sub_u32 s4, s4, 0x800
	s_cmpk_lt_u32 s4, 0x5800
	s_cbranch_scc1 .Lp0_c5_17
	s_sub_u32 s4, s4, 0x5800
	s_branch .Lp0_c6_18
.Lp0_c0_12:
	s_lshr_b32 s5, s4, 11
	s_and_b32 s6, s4, 0x7ff
	s_lshr_b32 s7, s6, 6
	s_and_b32 s8, s6, 63
	s_lshl_b32 s7, s7, 6
	s_lshl_b32 s8, s8, 6
	s_mov_b32 s9, s8
	s_mul_i32 s10, s7, 0x4000
	s_lshl_b32 s11, s8, 2
	s_add_u32 s10, s10, s11
	s_mul_i32 s11, s5, 0x2000000
	s_add_u32 s10, s10, s11
	s_add_u32 s60, s50, s10
	s_addc_u32 s61, s51, 0
	s_lshl_b32 s10, s5, 13
	s_lshl_b32 s11, s7, 2
	s_add_u32 s10, s10, s11
	s_add_u32 s62, s22, s10
	s_addc_u32 s63, s23, 0
	s_mov_b32 s68, 1
	s_mul_i32 s10, s9, 0x1000
	s_lshl_b32 s11, s7, 1
	s_add_u32 s10, s10, s11
	s_mul_i32 s11, s5, 0x1000000
	s_add_u32 s10, s10, s11
	s_add_u32 s10, s10, 0x600000
	s_add_u32 s64, s48, s10
	s_addc_u32 s65, s49, 0
	s_mov_b32 s66, 0x4000
	s_mov_b32 s67, 0x1000
	s_branch .Lp0_dec_done_11
.Lp0_c1_13:
	s_lshr_b32 s5, s4, 10
	s_and_b32 s6, s4, 0x3ff
	s_lshr_b32 s7, s6, 5
	s_and_b32 s8, s6, 31
	s_lshl_b32 s7, s7, 6
	s_lshl_b32 s8, s8, 6
	s_mov_b32 s9, s8
	s_mul_i32 s10, s7, 0x2000
	s_lshl_b32 s11, s8, 2
	s_add_u32 s10, s10, s11
	s_mul_i32 s11, s5, 0x1000000
	s_add_u32 s10, s10, s11
	s_add_u32 s60, s24, s10
	s_addc_u32 s61, s25, 0
	s_mov_b64 s[62:63], s[22:23]
	s_mov_b32 s68, 0
	s_mul_i32 s10, s9, 0x1000
	s_lshl_b32 s11, s7, 1
	s_add_u32 s10, s10, s11
	s_mul_i32 s11, s5, 0x800000
	s_add_u32 s10, s10, s11
	s_add_u32 s10, s10, 0x2600000
	s_add_u32 s64, s48, s10
	s_addc_u32 s65, s49, 0
	s_mov_b32 s66, 0x2000
	s_mov_b32 s67, 0x1000
	s_branch .Lp0_dec_done_11
.Lp0_c2_14:
	s_mov_b32 s5, 0
	s_mov_b32 s6, s4
	s_lshr_b32 s7, s6, 6
	s_and_b32 s8, s6, 63
	s_lshl_b32 s7, s7, 6
	s_lshl_b32 s8, s8, 6
	s_mov_b32 s9, s8
	s_mul_i32 s10, s7, 0x4040
	s_lshl_b32 s11, s8, 2
	s_add_u32 s10, s10, s11
	s_add_u32 s60, s52, s10
	s_addc_u32 s61, s53, 0
	s_lshl_b32 s10, s5, 13
	s_lshl_b32 s11, s7, 2
	s_add_u32 s10, s10, s11
	s_add_u32 s62, s26, s10
	s_addc_u32 s63, s27, 0
	s_mov_b32 s68, 1
	s_mul_i32 s10, s9, 0x1000
	s_lshl_b32 s11, s7, 1
	s_add_u32 s10, s10, s11
	s_add_u32 s10, s10, 0x3600000
	s_add_u32 s64, s48, s10
	s_addc_u32 s65, s49, 0
	s_mov_b32 s66, 0x4040
	s_mov_b32 s67, 0x1000
	s_branch .Lp0_dec_done_11
.Lp0_c3_15:
	s_lshr_b32 s5, s4, 11
	s_and_b32 s6, s4, 0x7ff
	s_lshr_b32 s7, s6, 6
	s_and_b32 s8, s6, 63
	s_lshl_b32 s7, s7, 6
	s_lshl_b32 s8, s8, 6
	s_mov_b32 s9, s8
	s_mul_i32 s10, s7, 0x4000
	s_lshl_b32 s11, s8, 2
	s_add_u32 s10, s10, s11
	s_mul_i32 s11, s5, 0x2000000
	s_add_u32 s10, s10, s11
	s_add_u32 s60, s30, s10
	s_addc_u32 s61, s31, 0
	s_lshl_b32 s10, s5, 13
	s_lshl_b32 s11, s7, 2
	s_add_u32 s10, s10, s11
	s_add_u32 s62, s28, s10
	s_addc_u32 s63, s29, 0
	s_mov_b32 s68, 1
	s_mul_i32 s10, s9, 0x1000
	s_lshl_b32 s11, s7, 1
	s_add_u32 s10, s10, s11
	s_mul_i32 s11, s5, 0x1000000
	s_add_u32 s10, s10, s11
	s_add_u32 s10, s10, 0x4600000
	s_add_u32 s64, s48, s10
	s_addc_u32 s65, s49, 0
	s_mov_b32 s66, 0x4000
	s_mov_b32 s67, 0x1000
	s_branch .Lp0_dec_done_11
.Lp0_c4_16:
	s_lshr_b32 s5, s4, 10
	s_and_b32 s6, s4, 0x3ff
	s_lshr_b32 s7, s6, 5
	s_and_b32 s8, s6, 31
	s_lshl_b32 s7, s7, 6
	s_lshl_b32 s8, s8, 6
	s_mov_b32 s9, s8
	s_mul_i32 s10, s7, 0x2000
	s_lshl_b32 s11, s8, 2
	s_add_u32 s10, s10, s11
	s_mul_i32 s11, s5, 0x1000000
	s_add_u32 s10, s10, s11
	s_add_u32 s60, s36, s10
	s_addc_u32 s61, s37, 0
	s_mov_b64 s[62:63], s[22:23]
	s_mov_b32 s68, 0
	s_mul_i32 s10, s9, 0x1000
	s_lshl_b32 s11, s7, 1
	s_add_u32 s10, s10, s11
	s_mul_i32 s11, s5, 0x800000
	s_add_u32 s10, s10, s11
	s_add_u32 s10, s10, 0x6600000
	s_add_u32 s64, s48, s10
	s_addc_u32 s65, s49, 0
	s_mov_b32 s66, 0x2000
	s_mov_b32 s67, 0x1000
	s_branch .Lp0_dec_done_11

.Lp0_uprow_done_20:
	s_mul_i32 s10, s7, 0xb000
	s_lshl_b32 s11, s8, 2
	s_add_u32 s10, s10, s11
	s_mul_i32 s11, s5, 0x5800000
	s_add_u32 s10, s10, s11
	s_add_u32 s60, s54, s10
	s_addc_u32 s61, s55, 0
	s_lshl_b32 s10, s5, 13
	s_lshl_b32 s11, s7, 2
	s_add_u32 s10, s10, s11
	s_add_u32 s62, s38, s10
	s_addc_u32 s63, s39, 0
	s_mov_b32 s68, 1
	s_mul_i32 s10, s9, 0x1000
	s_lshl_b32 s11, s7, 1
	s_add_u32 s10, s10, s11
	s_mul_i32 s11, s5, 0x2c00000
	s_add_u32 s10, s10, s11
	s_add_u32 s10, s10, 0x7600000
	s_add_u32 s64, s48, s10
	s_addc_u32 s65, s49, 0
	s_mov_b32 s66, 0xb000
	s_mov_b32 s67, 0x1000
	s_branch .Lp0_dec_done_11
.Lp0_c6_18:
	s_lshr_b32 s5, s4, 4
	s_mul_i32 s5, s5, 0x1746
	s_lshr_b32 s5, s5, 20
	s_mul_i32 s6, s5, 0xb00
	s_sub_u32 s6, s4, s6
	s_lshr_b32 s7, s6, 5
	s_and_b32 s8, s6, 31
	s_lshl_b32 s7, s7, 6
	s_lshl_b32 s8, s8, 6
	s_mov_b32 s9, s8
	s_mul_i32 s10, s7, 0x2000
	s_lshl_b32 s11, s8, 2
	s_add_u32 s10, s10, s11
	s_mul_i32 s11, s5, 0x2c00000
	s_add_u32 s10, s10, s11
	s_add_u32 s60, s56, s10
	s_addc_u32 s61, s57, 0
	s_mov_b64 s[62:63], s[22:23]
	s_mov_b32 s68, 0
	s_mul_i32 s10, s9, 0x2c00
	s_lshl_b32 s11, s7, 1
	s_add_u32 s10, s10, s11
	s_mul_i32 s11, s5, 0x1600000
	s_add_u32 s10, s10, s11
	s_add_u32 s10, s10, 0x12600000
	s_add_u32 s64, s48, s10
	s_addc_u32 s65, s49, 0
	s_mov_b32 s66, 0x2000
	s_mov_b32 s67, 0x2c00
.Lp0_dec_done_11:
	v_mad_u32_u24 v83, s66, v85, v86
	v_mad_u32_u24 v84, s67, v90, v91
	s_mov_b64 s[42:43], s[60:61]
	s_lshl_b32 s46, s66, 2
	global_load_dwordx4 v[2:5], v83, s[42:43]
	s_add_u32 s42, s42, s46
	s_addc_u32 s43, s43, 0
	global_load_dwordx4 v[6:9], v83, s[42:43]
	s_add_u32 s42, s42, s46
	s_addc_u32 s43, s43, 0
	global_load_dwordx4 v[10:13], v83, s[42:43]
	s_add_u32 s42, s42, s46
	s_addc_u32 s43, s43, 0
	global_load_dwordx4 v[14:17], v83, s[42:43]
	s_add_u32 s42, s42, s46
	s_addc_u32 s43, s43, 0
	global_load_dwordx4 v[18:21], v83, s[42:43]
	s_add_u32 s42, s42, s46
	s_addc_u32 s43, s43, 0
	global_load_dwordx4 v[22:25], v83, s[42:43]
	s_add_u32 s42, s42, s46
	s_addc_u32 s43, s43, 0
	global_load_dwordx4 v[26:29], v83, s[42:43]
	s_add_u32 s42, s42, s46
	s_addc_u32 s43, s43, 0
	global_load_dwordx4 v[30:33], v83, s[42:43]
	s_add_u32 s42, s42, s46
	s_addc_u32 s43, s43, 0
	global_load_dwordx4 v[34:37], v83, s[42:43]
	s_add_u32 s42, s42, s46
	s_addc_u32 s43, s43, 0
	global_load_dwordx4 v[38:41], v83, s[42:43]
	s_add_u32 s42, s42, s46
	s_addc_u32 s43, s43, 0
	global_load_dwordx4 v[42:45], v83, s[42:43]
	s_add_u32 s42, s42, s46
	s_addc_u32 s43, s43, 0
	global_load_dwordx4 v[46:49], v83, s[42:43]
	s_add_u32 s42, s42, s46
	s_addc_u32 s43, s43, 0
	global_load_dwordx4 v[50:53], v83, s[42:43]
	s_add_u32 s42, s42, s46
	s_addc_u32 s43, s43, 0
	global_load_dwordx4 v[54:57], v83, s[42:43]
	s_add_u32 s42, s42, s46
	s_addc_u32 s43, s43, 0
	global_load_dwordx4 v[58:61], v83, s[42:43]
	s_add_u32 s42, s42, s46
	s_addc_u32 s43, s43, 0
	global_load_dwordx4 v[62:65], v83, s[42:43]
	global_load_dword v67, v87, s[62:63]
	global_load_dword v68, v87, s[62:63] offset:16
	global_load_dword v69, v87, s[62:63] offset:32
	global_load_dword v70, v87, s[62:63] offset:48
	global_load_dword v71, v87, s[62:63] offset:64
	global_load_dword v72, v87, s[62:63] offset:80
	global_load_dword v73, v87, s[62:63] offset:96
	global_load_dword v74, v87, s[62:63] offset:112
	global_load_dword v75, v87, s[62:63] offset:128
	global_load_dword v76, v87, s[62:63] offset:144
	global_load_dword v77, v87, s[62:63] offset:160
	global_load_dword v78, v87, s[62:63] offset:176
	global_load_dword v79, v87, s[62:63] offset:192
	global_load_dword v80, v87, s[62:63] offset:208
	global_load_dword v81, v87, s[62:63] offset:224
	global_load_dword v82, v87, s[62:63] offset:240
	s_waitcnt vmcnt(32)
	s_cmp_lg_u32 s41, 0
	s_cbranch_scc1 .Lp0_gain_ok_21
	v_mov_b32_e32 v156, 1.0
	v_mov_b32_e32 v157, 1.0
	v_mov_b32_e32 v158, 1.0
	v_mov_b32_e32 v159, 1.0
	v_mov_b32_e32 v160, 1.0
	v_mov_b32_e32 v161, 1.0
	v_mov_b32_e32 v162, 1.0
	v_mov_b32_e32 v163, 1.0
	v_mov_b32_e32 v164, 1.0
	v_mov_b32_e32 v165, 1.0
	v_mov_b32_e32 v166, 1.0
	v_mov_b32_e32 v167, 1.0
	v_mov_b32_e32 v168, 1.0
	v_mov_b32_e32 v169, 1.0
	v_mov_b32_e32 v170, 1.0
	v_mov_b32_e32 v171, 1.0
.Lp0_gain_ok_21:
	v_mul_f32_e32 v92, v92, v156
	v_mul_f32_e32 v93, v93, v156
	v_mul_f32_e32 v94, v94, v156
	v_mul_f32_e32 v95, v95, v156
	ds_write_b32 v88, v92 offset:0
	ds_write_b32 v88, v93 offset:4
	ds_write_b32 v88, v94 offset:8
	ds_write_b32 v88, v95 offset:12
	v_mul_f32_e32 v96, v96, v157
	v_mul_f32_e32 v97, v97, v157
	v_mul_f32_e32 v98, v98, v157
	v_mul_f32_e32 v99, v99, v157
	ds_write_b32 v88, v96 offset:1040
	ds_write_b32 v88, v97 offset:1044
	ds_write_b32 v88, v98 offset:1048
	ds_write_b32 v88, v99 offset:1052
	v_mul_f32_e32 v100, v100, v158
	v_mul_f32_e32 v101, v101, v158
	v_mul_f32_e32 v102, v102, v158
	v_mul_f32_e32 v103, v103, v158
	ds_write_b32 v88, v100 offset:2080
	ds_write_b32 v88, v101 offset:2084
	ds_write_b32 v88, v102 offset:2088
	ds_write_b32 v88, v103 offset:2092
	v_mul_f32_e32 v104, v104, v159
	v_mul_f32_e32 v105, v105, v159
	v_mul_f32_e32 v106, v106, v159
	v_mul_f32_e32 v107, v107, v159
	ds_write_b32 v88, v104 offset:3120
	ds_write_b32 v88, v105 offset:3124
	ds_write_b32 v88, v106 offset:3128
	ds_write_b32 v88, v107 offset:3132
	v_mul_f32_e32 v108, v108, v160
	v_mul_f32_e32 v109, v109, v160
	v_mul_f32_e32 v110, v110, v160
	v_mul_f32_e32 v111, v111, v160
	ds_write_b32 v88, v108 offset:4160
	ds_write_b32 v88, v109 offset:4164
	ds_write_b32 v88, v110 offset:4168
	ds_write_b32 v88, v111 offset:4172
	v_mul_f32_e32 v112, v112, v161
	v_mul_f32_e32 v113, v113, v161
	v_mul_f32_e32 v114, v114, v161
	v_mul_f32_e32 v115, v115, v161
	ds_write_b32 v88, v112 offset:5200
	ds_write_b32 v88, v113 offset:5204
	ds_write_b32 v88, v114 offset:5208
	ds_write_b32 v88, v115 offset:5212
	v_mul_f32_e32 v116, v116, v162
	v_mul_f32_e32 v117, v117, v162
	v_mul_f32_e32 v118, v118, v162
	v_mul_f32_e32 v119, v119, v162
	ds_write_b32 v88, v116 offset:6240
	ds_write_b32 v88, v117 offset:6244
	ds_write_b32 v88, v118 offset:6248
	ds_write_b32 v88, v119 offset:6252
	v_mul_f32_e32 v120, v120, v163
	v_mul_f32_e32 v121, v121, v163
	v_mul_f32_e32 v122, v122, v163
	v_mul_f32_e32 v123, v123, v163
	ds_write_b32 v88, v120 offset:7280
	ds_write_b32 v88, v121 offset:7284
	ds_write_b32 v88, v122 offset:7288
	ds_write_b32 v88, v123 offset:7292
	v_mul_f32_e32 v124, v124, v164
	v_mul_f32_e32 v125, v125, v164
	v_mul_f32_e32 v126, v126, v164
	v_mul_f32_e32 v127, v127, v164
	ds_write_b32 v88, v124 offset:8320
	ds_write_b32 v88, v125 offset:8324
	ds_write_b32 v88, v126 offset:8328
	ds_write_b32 v88, v127 offset:8332
	v_mul_f32_e32 v128, v128, v165
	v_mul_f32_e32 v129, v129, v165
	v_mul_f32_e32 v130, v130, v165
	v_mul_f32_e32 v131, v131, v165
	ds_write_b32 v88, v128 offset:9360
	ds_write_b32 v88, v129 offset:9364
	ds_write_b32 v88, v130 offset:9368
	ds_write_b32 v88, v131 offset:9372
	v_mul_f32_e32 v132, v132, v166
	v_mul_f32_e32 v133, v133, v166
	v_mul_f32_e32 v134, v134, v166
	v_mul_f32_e32 v135, v135, v166
	ds_write_b32 v88, v132 offset:10400
	ds_write_b32 v88, v133 offset:10404
	ds_write_b32 v88, v134 offset:10408
	ds_write_b32 v88, v135 offset:10412
	v_mul_f32_e32 v136, v136, v167
	v_mul_f32_e32 v137, v137, v167
	v_mul_f32_e32 v138, v138, v167
	v_mul_f32_e32 v139, v139, v167
	ds_write_b32 v88, v136 offset:11440
	ds_write_b32 v88, v137 offset:11444
	ds_write_b32 v88, v138 offset:11448
	ds_write_b32 v88, v139 offset:11452
	v_mul_f32_e32 v140, v140, v168
	v_mul_f32_e32 v141, v141, v168
	v_mul_f32_e32 v142, v142, v168
	v_mul_f32_e32 v143, v143, v168
	ds_write_b32 v88, v140 offset:12480
	ds_write_b32 v88, v141 offset:12484
	ds_write_b32 v88, v142 offset:12488
	ds_write_b32 v88, v143 offset:12492
	v_mul_f32_e32 v144, v144, v169
	v_mul_f32_e32 v145, v145, v169
	v_mul_f32_e32 v146, v146, v169
	v_mul_f32_e32 v147, v147, v169
	ds_write_b32 v88, v144 offset:13520
	ds_write_b32 v88, v145 offset:13524
	ds_write_b32 v88, v146 offset:13528
	ds_write_b32 v88, v147 offset:13532
	v_mul_f32_e32 v148, v148, v170
	v_mul_f32_e32 v149, v149, v170
	v_mul_f32_e32 v150, v150, v170
	v_mul_f32_e32 v151, v151, v170
	ds_write_b32 v88, v148 offset:14560
	ds_write_b32 v88, v149 offset:14564
	ds_write_b32 v88, v150 offset:14568
	ds_write_b32 v88, v151 offset:14572
	v_mul_f32_e32 v152, v152, v171
	v_mul_f32_e32 v153, v153, v171
	v_mul_f32_e32 v154, v154, v171
	v_mul_f32_e32 v155, v155, v171
	ds_write_b32 v88, v152 offset:15600
	ds_write_b32 v88, v153 offset:15604
	ds_write_b32 v88, v154 offset:15608
	ds_write_b32 v88, v155 offset:15612
	ds_read_b32 v92, v89 offset:0
	ds_read_b32 v93, v89 offset:260
	ds_read_b32 v94, v89 offset:520
	ds_read_b32 v95, v89 offset:780
	ds_read_b32 v96, v89 offset:1040
	ds_read_b32 v97, v89 offset:1300
	ds_read_b32 v98, v89 offset:1560
	ds_read_b32 v99, v89 offset:1820
	ds_read_b32 v100, v89 offset:32
	ds_read_b32 v101, v89 offset:292
	ds_read_b32 v102, v89 offset:552
	ds_read_b32 v103, v89 offset:812
	ds_read_b32 v104, v89 offset:1072
	ds_read_b32 v105, v89 offset:1332
	ds_read_b32 v106, v89 offset:1592
	ds_read_b32 v107, v89 offset:1852
	ds_read_b32 v108, v89 offset:64
	ds_read_b32 v109, v89 offset:324
	ds_read_b32 v110, v89 offset:584
	ds_read_b32 v111, v89 offset:844
	ds_read_b32 v112, v89 offset:1104
	ds_read_b32 v113, v89 offset:1364
	ds_read_b32 v114, v89 offset:1624
	ds_read_b32 v115, v89 offset:1884
	ds_read_b32 v116, v89 offset:96
	ds_read_b32 v117, v89 offset:356
	ds_read_b32 v118, v89 offset:616
	ds_read_b32 v119, v89 offset:876
	ds_read_b32 v120, v89 offset:1136
	ds_read_b32 v121, v89 offset:1396
	ds_read_b32 v122, v89 offset:1656
	ds_read_b32 v123, v89 offset:1916
	ds_read_b32 v124, v89 offset:128
	ds_read_b32 v125, v89 offset:388
	ds_read_b32 v126, v89 offset:648
	ds_read_b32 v127, v89 offset:908
	ds_read_b32 v128, v89 offset:1168
	ds_read_b32 v129, v89 offset:1428
	ds_read_b32 v130, v89 offset:1688
	ds_read_b32 v131, v89 offset:1948
	ds_read_b32 v132, v89 offset:160
	ds_read_b32 v133, v89 offset:420
	ds_read_b32 v134, v89 offset:680
	ds_read_b32 v135, v89 offset:940
	ds_read_b32 v136, v89 offset:1200
	ds_read_b32 v137, v89 offset:1460
	ds_read_b32 v138, v89 offset:1720
	ds_read_b32 v139, v89 offset:1980
	ds_read_b32 v140, v89 offset:192
	ds_read_b32 v141, v89 offset:452
	ds_read_b32 v142, v89 offset:712
	ds_read_b32 v143, v89 offset:972
	ds_read_b32 v144, v89 offset:1232
	ds_read_b32 v145, v89 offset:1492
	ds_read_b32 v146, v89 offset:1752
	ds_read_b32 v147, v89 offset:2012
	ds_read_b32 v148, v89 offset:224
	ds_read_b32 v149, v89 offset:484
	ds_read_b32 v150, v89 offset:744
	ds_read_b32 v151, v89 offset:1004
	ds_read_b32 v152, v89 offset:1264
	ds_read_b32 v153, v89 offset:1524
	ds_read_b32 v154, v89 offset:1784
	ds_read_b32 v155, v89 offset:2044
	s_waitcnt lgkmcnt(0)
	s_mov_b64 s[42:43], s[18:19]
	s_lshl_b32 s46, s40, 3
	v_cvt_pk_bf16_f32 v92, v92, v93
	v_cvt_pk_bf16_f32 v93, v94, v95
	v_cvt_pk_bf16_f32 v94, v96, v97
	v_cvt_pk_bf16_f32 v95, v98, v99
	global_store_dwordx4 v173, v[92:95], s[42:43]
	s_add_u32 s42, s42, s46
	s_addc_u32 s43, s43, 0
	v_cvt_pk_bf16_f32 v100, v100, v101
	v_cvt_pk_bf16_f32 v101, v102, v103
	v_cvt_pk_bf16_f32 v102, v104, v105
	v_cvt_pk_bf16_f32 v103, v106, v107
	global_store_dwordx4 v173, v[100:103], s[42:43]
	s_add_u32 s42, s42, s46
	s_addc_u32 s43, s43, 0
	v_cvt_pk_bf16_f32 v108, v108, v109
	v_cvt_pk_bf16_f32 v109, v110, v111
	v_cvt_pk_bf16_f32 v110, v112, v113
	v_cvt_pk_bf16_f32 v111, v114, v115
	global_store_dwordx4 v173, v[108:111], s[42:43]
	s_add_u32 s42, s42, s46
	s_addc_u32 s43, s43, 0
	v_cvt_pk_bf16_f32 v116, v116, v117
	v_cvt_pk_bf16_f32 v117, v118, v119
	v_cvt_pk_bf16_f32 v118, v120, v121
	v_cvt_pk_bf16_f32 v119, v122, v123
	global_store_dwordx4 v173, v[116:119], s[42:43]
	s_add_u32 s42, s42, s46
	s_addc_u32 s43, s43, 0
	v_cvt_pk_bf16_f32 v124, v124, v125
	v_cvt_pk_bf16_f32 v125, v126, v127
	v_cvt_pk_bf16_f32 v126, v128, v129
	v_cvt_pk_bf16_f32 v127, v130, v131
	global_store_dwordx4 v173, v[124:127], s[42:43]
	s_add_u32 s42, s42, s46
	s_addc_u32 s43, s43, 0
	v_cvt_pk_bf16_f32 v132, v132, v133
	v_cvt_pk_bf16_f32 v133, v134, v135
	v_cvt_pk_bf16_f32 v134, v136, v137
	v_cvt_pk_bf16_f32 v135, v138, v139
	global_store_dwordx4 v173, v[132:135], s[42:43]
	s_add_u32 s42, s42, s46
	s_addc_u32 s43, s43, 0
	v_cvt_pk_bf16_f32 v140, v140, v141
	v_cvt_pk_bf16_f32 v141, v142, v143
	v_cvt_pk_bf16_f32 v142, v144, v145
	v_cvt_pk_bf16_f32 v143, v146, v147
	global_store_dwordx4 v173, v[140:143], s[42:43]
	s_add_u32 s42, s42, s46
	s_addc_u32 s43, s43, 0
	v_cvt_pk_bf16_f32 v148, v148, v149
	v_cvt_pk_bf16_f32 v149, v150, v151
	v_cvt_pk_bf16_f32 v150, v152, v153
	v_cvt_pk_bf16_f32 v151, v154, v155
	global_store_dwordx4 v173, v[148:151], s[42:43]
	s_add_u32 s58, s58, s59
	s_cmp_gt_u32 s58, 0xbbff
	s_cbranch_scc1 .Lp0_lastB
	s_mov_b32 s4, s58
	s_cmpk_lt_u32 s4, 0x1000
	s_cbranch_scc1 .Lp0_c0_23
	s_sub_u32 s4, s4, 0x1000
	s_cmpk_lt_u32 s4, 0x800
	s_cbranch_scc1 .Lp0_c1_24
	s_sub_u32 s4, s4, 0x800
	s_cmpk_lt_u32 s4, 0x800
	s_cbranch_scc1 .Lp0_c2_25
	s_sub_u32 s4, s4, 0x800
	s_cmpk_lt_u32 s4, 0x1000
	s_cbranch_scc1 .Lp0_c3_26
	s_sub_u32 s4, s4, 0x1000
	s_cmpk_lt_u32 s4, 0x800
	s_cbranch_scc1 .Lp0_c4_27
	s_sub_u32 s4, s4, 0x800
	s_cmpk_lt_u32 s4, 0x5800
	s_cbranch_scc1 .Lp0_c5_28
	s_sub_u32 s4, s4, 0x5800
	s_branch .Lp0_c6_29

.Lp0_dec_done_22:
	v_mad_u32_u24 v172, s33, v85, v86
	v_mad_u32_u24 v173, s40, v90, v91
	s_mov_b64 s[42:43], s[14:15]
	s_lshl_b32 s46, s33, 2
	global_load_dwordx4 v[92:95], v172, s[42:43]
	s_add_u32 s42, s42, s46
	s_addc_u32 s43, s43, 0
	global_load_dwordx4 v[96:99], v172, s[42:43]
	s_add_u32 s42, s42, s46
	s_addc_u32 s43, s43, 0
	global_load_dwordx4 v[100:103], v172, s[42:43]
	s_add_u32 s42, s42, s46
	s_addc_u32 s43, s43, 0
	global_load_dwordx4 v[104:107], v172, s[42:43]
	s_add_u32 s42, s42, s46
	s_addc_u32 s43, s43, 0
	global_load_dwordx4 v[108:111], v172, s[42:43]
	s_add_u32 s42, s42, s46
	s_addc_u32 s43, s43, 0
	global_load_dwordx4 v[112:115], v172, s[42:43]
	s_add_u32 s42, s42, s46
	s_addc_u32 s43, s43, 0
	global_load_dwordx4 v[116:119], v172, s[42:43]
	s_add_u32 s42, s42, s46
	s_addc_u32 s43, s43, 0
	global_load_dwordx4 v[120:123], v172, s[42:43]
	s_add_u32 s42, s42, s46
	s_addc_u32 s43, s43, 0
	global_load_dwordx4 v[124:127], v172, s[42:43]
	s_add_u32 s42, s42, s46
	s_addc_u32 s43, s43, 0
	global_load_dwordx4 v[128:131], v172, s[42:43]
	s_add_u32 s42, s42, s46
	s_addc_u32 s43, s43, 0
	global_load_dwordx4 v[132:135], v172, s[42:43]
	s_add_u32 s42, s42, s46
	s_addc_u32 s43, s43, 0
	global_load_dwordx4 v[136:139], v172, s[42:43]
	s_add_u32 s42, s42, s46
	s_addc_u32 s43, s43, 0
	global_load_dwordx4 v[140:143], v172, s[42:43]
	s_add_u32 s42, s42, s46
	s_addc_u32 s43, s43, 0
	global_load_dwordx4 v[144:147], v172, s[42:43]
	s_add_u32 s42, s42, s46
	s_addc_u32 s43, s43, 0
	global_load_dwordx4 v[148:151], v172, s[42:43]
	s_add_u32 s42, s42, s46
	s_addc_u32 s43, s43, 0
	global_load_dwordx4 v[152:155], v172, s[42:43]
	global_load_dword v156, v87, s[16:17]
	global_load_dword v157, v87, s[16:17] offset:16
	global_load_dword v158, v87, s[16:17] offset:32
	global_load_dword v159, v87, s[16:17] offset:48
	global_load_dword v160, v87, s[16:17] offset:64
	global_load_dword v161, v87, s[16:17] offset:80
	global_load_dword v162, v87, s[16:17] offset:96
	global_load_dword v163, v87, s[16:17] offset:112
	global_load_dword v164, v87, s[16:17] offset:128
	global_load_dword v165, v87, s[16:17] offset:144
	global_load_dword v166, v87, s[16:17] offset:160
	global_load_dword v167, v87, s[16:17] offset:176
	global_load_dword v168, v87, s[16:17] offset:192
	global_load_dword v169, v87, s[16:17] offset:208
	global_load_dword v170, v87, s[16:17] offset:224
	global_load_dword v171, v87, s[16:17] offset:240
	s_waitcnt vmcnt(32)
	s_cmp_lg_u32 s68, 0
	s_cbranch_scc1 .Lp0_gain_ok_32
	v_mov_b32_e32 v67, 1.0
	v_mov_b32_e32 v68, 1.0
	v_mov_b32_e32 v69, 1.0
	v_mov_b32_e32 v70, 1.0
	v_mov_b32_e32 v71, 1.0
	v_mov_b32_e32 v72, 1.0
	v_mov_b32_e32 v73, 1.0
	v_mov_b32_e32 v74, 1.0
	v_mov_b32_e32 v75, 1.0
	v_mov_b32_e32 v76, 1.0
	v_mov_b32_e32 v77, 1.0
	v_mov_b32_e32 v78, 1.0
	v_mov_b32_e32 v79, 1.0
	v_mov_b32_e32 v80, 1.0
	v_mov_b32_e32 v81, 1.0
	v_mov_b32_e32 v82, 1.0
.Lp0_gain_ok_32:
	v_mul_f32_e32 v2, v2, v67
	v_mul_f32_e32 v3, v3, v67
	v_mul_f32_e32 v4, v4, v67
	v_mul_f32_e32 v5, v5, v67
	ds_write_b32 v88, v2 offset:0
	ds_write_b32 v88, v3 offset:4
	ds_write_b32 v88, v4 offset:8
	ds_write_b32 v88, v5 offset:12
	v_mul_f32_e32 v6, v6, v68
	v_mul_f32_e32 v7, v7, v68
	v_mul_f32_e32 v8, v8, v68
	v_mul_f32_e32 v9, v9, v68
	ds_write_b32 v88, v6 offset:1040
	ds_write_b32 v88, v7 offset:1044
	ds_write_b32 v88, v8 offset:1048
	ds_write_b32 v88, v9 offset:1052
	v_mul_f32_e32 v10, v10, v69
	v_mul_f32_e32 v11, v11, v69
	v_mul_f32_e32 v12, v12, v69
	v_mul_f32_e32 v13, v13, v69
	ds_write_b32 v88, v10 offset:2080
	ds_write_b32 v88, v11 offset:2084
	ds_write_b32 v88, v12 offset:2088
	ds_write_b32 v88, v13 offset:2092
	v_mul_f32_e32 v14, v14, v70
	v_mul_f32_e32 v15, v15, v70
	v_mul_f32_e32 v16, v16, v70
	v_mul_f32_e32 v17, v17, v70
	ds_write_b32 v88, v14 offset:3120
	ds_write_b32 v88, v15 offset:3124
	ds_write_b32 v88, v16 offset:3128
	ds_write_b32 v88, v17 offset:3132
	v_mul_f32_e32 v18, v18, v71
	v_mul_f32_e32 v19, v19, v71
	v_mul_f32_e32 v20, v20, v71
	v_mul_f32_e32 v21, v21, v71
	ds_write_b32 v88, v18 offset:4160
	ds_write_b32 v88, v19 offset:4164
	ds_write_b32 v88, v20 offset:4168
	ds_write_b32 v88, v21 offset:4172
	v_mul_f32_e32 v22, v22, v72
	v_mul_f32_e32 v23, v23, v72
	v_mul_f32_e32 v24, v24, v72
	v_mul_f32_e32 v25, v25, v72
	ds_write_b32 v88, v22 offset:5200
	ds_write_b32 v88, v23 offset:5204
	ds_write_b32 v88, v24 offset:5208
	ds_write_b32 v88, v25 offset:5212
	v_mul_f32_e32 v26, v26, v73
	v_mul_f32_e32 v27, v27, v73
	v_mul_f32_e32 v28, v28, v73
	v_mul_f32_e32 v29, v29, v73
	ds_write_b32 v88, v26 offset:6240
	ds_write_b32 v88, v27 offset:6244
	ds_write_b32 v88, v28 offset:6248
	ds_write_b32 v88, v29 offset:6252
	v_mul_f32_e32 v30, v30, v74
	v_mul_f32_e32 v31, v31, v74
	v_mul_f32_e32 v32, v32, v74
	v_mul_f32_e32 v33, v33, v74
	ds_write_b32 v88, v30 offset:7280
	ds_write_b32 v88, v31 offset:7284
	ds_write_b32 v88, v32 offset:7288
	ds_write_b32 v88, v33 offset:7292
	v_mul_f32_e32 v34, v34, v75
	v_mul_f32_e32 v35, v35, v75
	v_mul_f32_e32 v36, v36, v75
	v_mul_f32_e32 v37, v37, v75
	ds_write_b32 v88, v34 offset:8320
	ds_write_b32 v88, v35 offset:8324
	ds_write_b32 v88, v36 offset:8328
	ds_write_b32 v88, v37 offset:8332
	v_mul_f32_e32 v38, v38, v76
	v_mul_f32_e32 v39, v39, v76
	v_mul_f32_e32 v40, v40, v76
	v_mul_f32_e32 v41, v41, v76
	ds_write_b32 v88, v38 offset:9360
	ds_write_b32 v88, v39 offset:9364
	ds_write_b32 v88, v40 offset:9368
	ds_write_b32 v88, v41 offset:9372
	v_mul_f32_e32 v42, v42, v77
	v_mul_f32_e32 v43, v43, v77
	v_mul_f32_e32 v44, v44, v77
	v_mul_f32_e32 v45, v45, v77
	ds_write_b32 v88, v42 offset:10400
	ds_write_b32 v88, v43 offset:10404
	ds_write_b32 v88, v44 offset:10408
	ds_write_b32 v88, v45 offset:10412
	v_mul_f32_e32 v46, v46, v78
	v_mul_f32_e32 v47, v47, v78
	v_mul_f32_e32 v48, v48, v78
	v_mul_f32_e32 v49, v49, v78
	ds_write_b32 v88, v46 offset:11440
	ds_write_b32 v88, v47 offset:11444
	ds_write_b32 v88, v48 offset:11448
	ds_write_b32 v88, v49 offset:11452
	v_mul_f32_e32 v50, v50, v79
	v_mul_f32_e32 v51, v51, v79
	v_mul_f32_e32 v52, v52, v79
	v_mul_f32_e32 v53, v53, v79
	ds_write_b32 v88, v50 offset:12480
	ds_write_b32 v88, v51 offset:12484
	ds_write_b32 v88, v52 offset:12488
	ds_write_b32 v88, v53 offset:12492
	v_mul_f32_e32 v54, v54, v80
	v_mul_f32_e32 v55, v55, v80
	v_mul_f32_e32 v56, v56, v80
	v_mul_f32_e32 v57, v57, v80
	ds_write_b32 v88, v54 offset:13520
	ds_write_b32 v88, v55 offset:13524
	ds_write_b32 v88, v56 offset:13528
	ds_write_b32 v88, v57 offset:13532
	v_mul_f32_e32 v58, v58, v81
	v_mul_f32_e32 v59, v59, v81
	v_mul_f32_e32 v60, v60, v81
	v_mul_f32_e32 v61, v61, v81
	ds_write_b32 v88, v58 offset:14560
	ds_write_b32 v88, v59 offset:14564
	ds_write_b32 v88, v60 offset:14568
	ds_write_b32 v88, v61 offset:14572
	v_mul_f32_e32 v62, v62, v82
	v_mul_f32_e32 v63, v63, v82
	v_mul_f32_e32 v64, v64, v82
	v_mul_f32_e32 v65, v65, v82
	ds_write_b32 v88, v62 offset:15600
	ds_write_b32 v88, v63 offset:15604
	ds_write_b32 v88, v64 offset:15608
	ds_write_b32 v88, v65 offset:15612
	ds_read_b32 v2, v89 offset:0
	ds_read_b32 v3, v89 offset:260
	ds_read_b32 v4, v89 offset:520
	ds_read_b32 v5, v89 offset:780
	ds_read_b32 v6, v89 offset:1040
	ds_read_b32 v7, v89 offset:1300
	ds_read_b32 v8, v89 offset:1560
	ds_read_b32 v9, v89 offset:1820
	ds_read_b32 v10, v89 offset:32
	ds_read_b32 v11, v89 offset:292
	ds_read_b32 v12, v89 offset:552
	ds_read_b32 v13, v89 offset:812
	ds_read_b32 v14, v89 offset:1072
	ds_read_b32 v15, v89 offset:1332
	ds_read_b32 v16, v89 offset:1592
	ds_read_b32 v17, v89 offset:1852
	ds_read_b32 v18, v89 offset:64
	ds_read_b32 v19, v89 offset:324
	ds_read_b32 v20, v89 offset:584
	ds_read_b32 v21, v89 offset:844
	ds_read_b32 v22, v89 offset:1104
	ds_read_b32 v23, v89 offset:1364
	ds_read_b32 v24, v89 offset:1624
	ds_read_b32 v25, v89 offset:1884
	ds_read_b32 v26, v89 offset:96
	ds_read_b32 v27, v89 offset:356
	ds_read_b32 v28, v89 offset:616
	ds_read_b32 v29, v89 offset:876
	ds_read_b32 v30, v89 offset:1136
	ds_read_b32 v31, v89 offset:1396
	ds_read_b32 v32, v89 offset:1656
	ds_read_b32 v33, v89 offset:1916
	ds_read_b32 v34, v89 offset:128
	ds_read_b32 v35, v89 offset:388
	ds_read_b32 v36, v89 offset:648
	ds_read_b32 v37, v89 offset:908
	ds_read_b32 v38, v89 offset:1168
	ds_read_b32 v39, v89 offset:1428
	ds_read_b32 v40, v89 offset:1688
	ds_read_b32 v41, v89 offset:1948
	ds_read_b32 v42, v89 offset:160
	ds_read_b32 v43, v89 offset:420
	ds_read_b32 v44, v89 offset:680
	ds_read_b32 v45, v89 offset:940
	ds_read_b32 v46, v89 offset:1200
	ds_read_b32 v47, v89 offset:1460
	ds_read_b32 v48, v89 offset:1720
	ds_read_b32 v49, v89 offset:1980
	ds_read_b32 v50, v89 offset:192
	ds_read_b32 v51, v89 offset:452
	ds_read_b32 v52, v89 offset:712
	ds_read_b32 v53, v89 offset:972
	ds_read_b32 v54, v89 offset:1232
	ds_read_b32 v55, v89 offset:1492
	ds_read_b32 v56, v89 offset:1752
	ds_read_b32 v57, v89 offset:2012
	ds_read_b32 v58, v89 offset:224
	ds_read_b32 v59, v89 offset:484
	ds_read_b32 v60, v89 offset:744
	ds_read_b32 v61, v89 offset:1004
	ds_read_b32 v62, v89 offset:1264
	ds_read_b32 v63, v89 offset:1524
	ds_read_b32 v64, v89 offset:1784
	ds_read_b32 v65, v89 offset:2044
	s_waitcnt lgkmcnt(0)
	s_mov_b64 s[42:43], s[64:65]
	s_lshl_b32 s46, s67, 3
	v_cvt_pk_bf16_f32 v2, v2, v3
	v_cvt_pk_bf16_f32 v3, v4, v5
	v_cvt_pk_bf16_f32 v4, v6, v7
	v_cvt_pk_bf16_f32 v5, v8, v9
	global_store_dwordx4 v84, v[2:5], s[42:43]
	s_add_u32 s42, s42, s46
	s_addc_u32 s43, s43, 0
	v_cvt_pk_bf16_f32 v10, v10, v11
	v_cvt_pk_bf16_f32 v11, v12, v13
	v_cvt_pk_bf16_f32 v12, v14, v15
	v_cvt_pk_bf16_f32 v13, v16, v17
	global_store_dwordx4 v84, v[10:13], s[42:43]
	s_add_u32 s42, s42, s46
	s_addc_u32 s43, s43, 0
	v_cvt_pk_bf16_f32 v18, v18, v19
	v_cvt_pk_bf16_f32 v19, v20, v21
	v_cvt_pk_bf16_f32 v20, v22, v23
	v_cvt_pk_bf16_f32 v21, v24, v25
	global_store_dwordx4 v84, v[18:21], s[42:43]
	s_add_u32 s42, s42, s46
	s_addc_u32 s43, s43, 0
	v_cvt_pk_bf16_f32 v26, v26, v27
	v_cvt_pk_bf16_f32 v27, v28, v29
	v_cvt_pk_bf16_f32 v28, v30, v31
	v_cvt_pk_bf16_f32 v29, v32, v33
	global_store_dwordx4 v84, v[26:29], s[42:43]
	s_add_u32 s42, s42, s46
	s_addc_u32 s43, s43, 0
	v_cvt_pk_bf16_f32 v34, v34, v35
	v_cvt_pk_bf16_f32 v35, v36, v37
	v_cvt_pk_bf16_f32 v36, v38, v39
	v_cvt_pk_bf16_f32 v37, v40, v41
	global_store_dwordx4 v84, v[34:37], s[42:43]
	s_add_u32 s42, s42, s46
	s_addc_u32 s43, s43, 0
	v_cvt_pk_bf16_f32 v42, v42, v43
	v_cvt_pk_bf16_f32 v43, v44, v45
	v_cvt_pk_bf16_f32 v44, v46, v47
	v_cvt_pk_bf16_f32 v45, v48, v49
	global_store_dwordx4 v84, v[42:45], s[42:43]
	s_add_u32 s42, s42, s46
	s_addc_u32 s43, s43, 0
	v_cvt_pk_bf16_f32 v50, v50, v51
	v_cvt_pk_bf16_f32 v51, v52, v53
	v_cvt_pk_bf16_f32 v52, v54, v55
	v_cvt_pk_bf16_f32 v53, v56, v57
	global_store_dwordx4 v84, v[50:53], s[42:43]
	s_add_u32 s42, s42, s46
	s_addc_u32 s43, s43, 0
	v_cvt_pk_bf16_f32 v58, v58, v59
	v_cvt_pk_bf16_f32 v59, v60, v61
	v_cvt_pk_bf16_f32 v60, v62, v63
	v_cvt_pk_bf16_f32 v61, v64, v65
	global_store_dwordx4 v84, v[58:61], s[42:43]
	s_branch .Lp0_top
.Lp0_lastA:
	s_waitcnt vmcnt(0)
	s_cmp_lg_u32 s41, 0
	s_cbranch_scc1 .Lp0_gain_ok_33
	v_mov_b32_e32 v156, 1.0
	v_mov_b32_e32 v157, 1.0
	v_mov_b32_e32 v158, 1.0
	v_mov_b32_e32 v159, 1.0
	v_mov_b32_e32 v160, 1.0
	v_mov_b32_e32 v161, 1.0
	v_mov_b32_e32 v162, 1.0
	v_mov_b32_e32 v163, 1.0
	v_mov_b32_e32 v164, 1.0
	v_mov_b32_e32 v165, 1.0
	v_mov_b32_e32 v166, 1.0
	v_mov_b32_e32 v167, 1.0
	v_mov_b32_e32 v168, 1.0
	v_mov_b32_e32 v169, 1.0
	v_mov_b32_e32 v170, 1.0
	v_mov_b32_e32 v171, 1.0
.Lp0_gain_ok_33:
	v_mul_f32_e32 v92, v92, v156
	v_mul_f32_e32 v93, v93, v156
	v_mul_f32_e32 v94, v94, v156
	v_mul_f32_e32 v95, v95, v156
	ds_write_b32 v88, v92 offset:0
	ds_write_b32 v88, v93 offset:4
	ds_write_b32 v88, v94 offset:8
	ds_write_b32 v88, v95 offset:12
	v_mul_f32_e32 v96, v96, v157
	v_mul_f32_e32 v97, v97, v157
	v_mul_f32_e32 v98, v98, v157
	v_mul_f32_e32 v99, v99, v157
	ds_write_b32 v88, v96 offset:1040
	ds_write_b32 v88, v97 offset:1044
	ds_write_b32 v88, v98 offset:1048
	ds_write_b32 v88, v99 offset:1052
	v_mul_f32_e32 v100, v100, v158
	v_mul_f32_e32 v101, v101, v158
	v_mul_f32_e32 v102, v102, v158
	v_mul_f32_e32 v103, v103, v158
	ds_write_b32 v88, v100 offset:2080
	ds_write_b32 v88, v101 offset:2084
	ds_write_b32 v88, v102 offset:2088
	ds_write_b32 v88, v103 offset:2092
	v_mul_f32_e32 v104, v104, v159
	v_mul_f32_e32 v105, v105, v159
	v_mul_f32_e32 v106, v106, v159
	v_mul_f32_e32 v107, v107, v159
	ds_write_b32 v88, v104 offset:3120
	ds_write_b32 v88, v105 offset:3124
	ds_write_b32 v88, v106 offset:3128
	ds_write_b32 v88, v107 offset:3132
	v_mul_f32_e32 v108, v108, v160
	v_mul_f32_e32 v109, v109, v160
	v_mul_f32_e32 v110, v110, v160
	v_mul_f32_e32 v111, v111, v160
	ds_write_b32 v88, v108 offset:4160
	ds_write_b32 v88, v109 offset:4164
	ds_write_b32 v88, v110 offset:4168
	ds_write_b32 v88, v111 offset:4172
	v_mul_f32_e32 v112, v112, v161
	v_mul_f32_e32 v113, v113, v161
	v_mul_f32_e32 v114, v114, v161
	v_mul_f32_e32 v115, v115, v161
	ds_write_b32 v88, v112 offset:5200
	ds_write_b32 v88, v113 offset:5204
	ds_write_b32 v88, v114 offset:5208
	ds_write_b32 v88, v115 offset:5212
	v_mul_f32_e32 v116, v116, v162
	v_mul_f32_e32 v117, v117, v162
	v_mul_f32_e32 v118, v118, v162
	v_mul_f32_e32 v119, v119, v162
	ds_write_b32 v88, v116 offset:6240
	ds_write_b32 v88, v117 offset:6244
	ds_write_b32 v88, v118 offset:6248
	ds_write_b32 v88, v119 offset:6252
	v_mul_f32_e32 v120, v120, v163
	v_mul_f32_e32 v121, v121, v163
	v_mul_f32_e32 v122, v122, v163
	v_mul_f32_e32 v123, v123, v163
	ds_write_b32 v88, v120 offset:7280
	ds_write_b32 v88, v121 offset:7284
	ds_write_b32 v88, v122 offset:7288
	ds_write_b32 v88, v123 offset:7292
	v_mul_f32_e32 v124, v124, v164
	v_mul_f32_e32 v125, v125, v164
	v_mul_f32_e32 v126, v126, v164
	v_mul_f32_e32 v127, v127, v164
	ds_write_b32 v88, v124 offset:8320
	ds_write_b32 v88, v125 offset:8324
	ds_write_b32 v88, v126 offset:8328
	ds_write_b32 v88, v127 offset:8332
	v_mul_f32_e32 v128, v128, v165
	v_mul_f32_e32 v129, v129, v165
	v_mul_f32_e32 v130, v130, v165
	v_mul_f32_e32 v131, v131, v165
	ds_write_b32 v88, v128 offset:9360
	ds_write_b32 v88, v129 offset:9364
	ds_write_b32 v88, v130 offset:9368
	ds_write_b32 v88, v131 offset:9372
	v_mul_f32_e32 v132, v132, v166
	v_mul_f32_e32 v133, v133, v166
	v_mul_f32_e32 v134, v134, v166
	v_mul_f32_e32 v135, v135, v166
	ds_write_b32 v88, v132 offset:10400
	ds_write_b32 v88, v133 offset:10404
	ds_write_b32 v88, v134 offset:10408
	ds_write_b32 v88, v135 offset:10412
	v_mul_f32_e32 v136, v136, v167
	v_mul_f32_e32 v137, v137, v167
	v_mul_f32_e32 v138, v138, v167
	v_mul_f32_e32 v139, v139, v167
	ds_write_b32 v88, v136 offset:11440
	ds_write_b32 v88, v137 offset:11444
	ds_write_b32 v88, v138 offset:11448
	ds_write_b32 v88, v139 offset:11452
	v_mul_f32_e32 v140, v140, v168
	v_mul_f32_e32 v141, v141, v168
	v_mul_f32_e32 v142, v142, v168
	v_mul_f32_e32 v143, v143, v168
	ds_write_b32 v88, v140 offset:12480
	ds_write_b32 v88, v141 offset:12484
	ds_write_b32 v88, v142 offset:12488
	ds_write_b32 v88, v143 offset:12492
	v_mul_f32_e32 v144, v144, v169
	v_mul_f32_e32 v145, v145, v169
	v_mul_f32_e32 v146, v146, v169
	v_mul_f32_e32 v147, v147, v169
	ds_write_b32 v88, v144 offset:13520
	ds_write_b32 v88, v145 offset:13524
	ds_write_b32 v88, v146 offset:13528
	ds_write_b32 v88, v147 offset:13532
	v_mul_f32_e32 v148, v148, v170
	v_mul_f32_e32 v149, v149, v170
	v_mul_f32_e32 v150, v150, v170
	v_mul_f32_e32 v151, v151, v170
	ds_write_b32 v88, v148 offset:14560
	ds_write_b32 v88, v149 offset:14564
	ds_write_b32 v88, v150 offset:14568
	ds_write_b32 v88, v151 offset:14572
	v_mul_f32_e32 v152, v152, v171
	v_mul_f32_e32 v153, v153, v171
	v_mul_f32_e32 v154, v154, v171
	v_mul_f32_e32 v155, v155, v171
	ds_write_b32 v88, v152 offset:15600
	ds_write_b32 v88, v153 offset:15604
	ds_write_b32 v88, v154 offset:15608
	ds_write_b32 v88, v155 offset:15612
	ds_read_b32 v92, v89 offset:0
	ds_read_b32 v93, v89 offset:260
	ds_read_b32 v94, v89 offset:520
	ds_read_b32 v95, v89 offset:780
	ds_read_b32 v96, v89 offset:1040
	ds_read_b32 v97, v89 offset:1300
	ds_read_b32 v98, v89 offset:1560
	ds_read_b32 v99, v89 offset:1820
	ds_read_b32 v100, v89 offset:32
	ds_read_b32 v101, v89 offset:292
	ds_read_b32 v102, v89 offset:552
	ds_read_b32 v103, v89 offset:812
	ds_read_b32 v104, v89 offset:1072
	ds_read_b32 v105, v89 offset:1332
	ds_read_b32 v106, v89 offset:1592
	ds_read_b32 v107, v89 offset:1852
	ds_read_b32 v108, v89 offset:64
	ds_read_b32 v109, v89 offset:324
	ds_read_b32 v110, v89 offset:584
	ds_read_b32 v111, v89 offset:844
	ds_read_b32 v112, v89 offset:1104
	ds_read_b32 v113, v89 offset:1364
	ds_read_b32 v114, v89 offset:1624
	ds_read_b32 v115, v89 offset:1884
	ds_read_b32 v116, v89 offset:96
	ds_read_b32 v117, v89 offset:356
	ds_read_b32 v118, v89 offset:616
	ds_read_b32 v119, v89 offset:876
	ds_read_b32 v120, v89 offset:1136
	ds_read_b32 v121, v89 offset:1396
	ds_read_b32 v122, v89 offset:1656
	ds_read_b32 v123, v89 offset:1916
	ds_read_b32 v124, v89 offset:128
	ds_read_b32 v125, v89 offset:388
	ds_read_b32 v126, v89 offset:648
	ds_read_b32 v127, v89 offset:908
	ds_read_b32 v128, v89 offset:1168
	ds_read_b32 v129, v89 offset:1428
	ds_read_b32 v130, v89 offset:1688
	ds_read_b32 v131, v89 offset:1948
	ds_read_b32 v132, v89 offset:160
	ds_read_b32 v133, v89 offset:420
	ds_read_b32 v134, v89 offset:680
	ds_read_b32 v135, v89 offset:940
	ds_read_b32 v136, v89 offset:1200
	ds_read_b32 v137, v89 offset:1460
	ds_read_b32 v138, v89 offset:1720
	ds_read_b32 v139, v89 offset:1980
	ds_read_b32 v140, v89 offset:192
	ds_read_b32 v141, v89 offset:452
	ds_read_b32 v142, v89 offset:712
	ds_read_b32 v143, v89 offset:972
	ds_read_b32 v144, v89 offset:1232
	ds_read_b32 v145, v89 offset:1492
	ds_read_b32 v146, v89 offset:1752
	ds_read_b32 v147, v89 offset:2012
	ds_read_b32 v148, v89 offset:224
	ds_read_b32 v149, v89 offset:484
	ds_read_b32 v150, v89 offset:744
	ds_read_b32 v151, v89 offset:1004
	ds_read_b32 v152, v89 offset:1264
	ds_read_b32 v153, v89 offset:1524
	ds_read_b32 v154, v89 offset:1784
	ds_read_b32 v155, v89 offset:2044
	s_waitcnt lgkmcnt(0)
	s_mov_b64 s[42:43], s[18:19]
	s_lshl_b32 s46, s40, 3
	v_cvt_pk_bf16_f32 v92, v92, v93
	v_cvt_pk_bf16_f32 v93, v94, v95
	v_cvt_pk_bf16_f32 v94, v96, v97
	v_cvt_pk_bf16_f32 v95, v98, v99
	global_store_dwordx4 v173, v[92:95], s[42:43]
	s_add_u32 s42, s42, s46
	s_addc_u32 s43, s43, 0
	v_cvt_pk_bf16_f32 v100, v100, v101
	v_cvt_pk_bf16_f32 v101, v102, v103
	v_cvt_pk_bf16_f32 v102, v104, v105
	v_cvt_pk_bf16_f32 v103, v106, v107
	global_store_dwordx4 v173, v[100:103], s[42:43]
	s_add_u32 s42, s42, s46
	s_addc_u32 s43, s43, 0
	v_cvt_pk_bf16_f32 v108, v108, v109
	v_cvt_pk_bf16_f32 v109, v110, v111
	v_cvt_pk_bf16_f32 v110, v112, v113
	v_cvt_pk_bf16_f32 v111, v114, v115
	global_store_dwordx4 v173, v[108:111], s[42:43]
	s_add_u32 s42, s42, s46
	s_addc_u32 s43, s43, 0
	v_cvt_pk_bf16_f32 v116, v116, v117
	v_cvt_pk_bf16_f32 v117, v118, v119
	v_cvt_pk_bf16_f32 v118, v120, v121
	v_cvt_pk_bf16_f32 v119, v122, v123
	global_store_dwordx4 v173, v[116:119], s[42:43]
	s_add_u32 s42, s42, s46
	s_addc_u32 s43, s43, 0
	v_cvt_pk_bf16_f32 v124, v124, v125
	v_cvt_pk_bf16_f32 v125, v126, v127
	v_cvt_pk_bf16_f32 v126, v128, v129
	v_cvt_pk_bf16_f32 v127, v130, v131
	global_store_dwordx4 v173, v[124:127], s[42:43]
	s_add_u32 s42, s42, s46
	s_addc_u32 s43, s43, 0
	v_cvt_pk_bf16_f32 v132, v132, v133
	v_cvt_pk_bf16_f32 v133, v134, v135
	v_cvt_pk_bf16_f32 v134, v136, v137
	v_cvt_pk_bf16_f32 v135, v138, v139
	global_store_dwordx4 v173, v[132:135], s[42:43]
	s_add_u32 s42, s42, s46
	s_addc_u32 s43, s43, 0
	v_cvt_pk_bf16_f32 v140, v140, v141
	v_cvt_pk_bf16_f32 v141, v142, v143
	v_cvt_pk_bf16_f32 v142, v144, v145
	v_cvt_pk_bf16_f32 v143, v146, v147
	global_store_dwordx4 v173, v[140:143], s[42:43]
	s_add_u32 s42, s42, s46
	s_addc_u32 s43, s43, 0
	v_cvt_pk_bf16_f32 v148, v148, v149
	v_cvt_pk_bf16_f32 v149, v150, v151
	v_cvt_pk_bf16_f32 v150, v152, v153
	v_cvt_pk_bf16_f32 v151, v154, v155
	global_store_dwordx4 v173, v[148:151], s[42:43]
	s_branch .Lp0_done
.Lp0_lastB:
	s_waitcnt vmcnt(0)
	s_cmp_lg_u32 s68, 0
	s_cbranch_scc1 .Lp0_gain_ok_34
	v_mov_b32_e32 v67, 1.0
	v_mov_b32_e32 v68, 1.0
	v_mov_b32_e32 v69, 1.0
	v_mov_b32_e32 v70, 1.0
	v_mov_b32_e32 v71, 1.0
	v_mov_b32_e32 v72, 1.0
	v_mov_b32_e32 v73, 1.0
	v_mov_b32_e32 v74, 1.0
	v_mov_b32_e32 v75, 1.0
	v_mov_b32_e32 v76, 1.0
	v_mov_b32_e32 v77, 1.0
	v_mov_b32_e32 v78, 1.0
	v_mov_b32_e32 v79, 1.0
	v_mov_b32_e32 v80, 1.0
	v_mov_b32_e32 v81, 1.0
	v_mov_b32_e32 v82, 1.0
.Lp0_gain_ok_34:
	v_mul_f32_e32 v2, v2, v67
	v_mul_f32_e32 v3, v3, v67
	v_mul_f32_e32 v4, v4, v67
	v_mul_f32_e32 v5, v5, v67
	ds_write_b32 v88, v2 offset:0
	ds_write_b32 v88, v3 offset:4
	ds_write_b32 v88, v4 offset:8
	ds_write_b32 v88, v5 offset:12
	v_mul_f32_e32 v6, v6, v68
	v_mul_f32_e32 v7, v7, v68
	v_mul_f32_e32 v8, v8, v68
	v_mul_f32_e32 v9, v9, v68
	ds_write_b32 v88, v6 offset:1040
	ds_write_b32 v88, v7 offset:1044
	ds_write_b32 v88, v8 offset:1048
	ds_write_b32 v88, v9 offset:1052
	v_mul_f32_e32 v10, v10, v69
	v_mul_f32_e32 v11, v11, v69
	v_mul_f32_e32 v12, v12, v69
	v_mul_f32_e32 v13, v13, v69
	ds_write_b32 v88, v10 offset:2080
	ds_write_b32 v88, v11 offset:2084
	ds_write_b32 v88, v12 offset:2088
	ds_write_b32 v88, v13 offset:2092
	v_mul_f32_e32 v14, v14, v70
	v_mul_f32_e32 v15, v15, v70
	v_mul_f32_e32 v16, v16, v70
	v_mul_f32_e32 v17, v17, v70
	ds_write_b32 v88, v14 offset:3120
	ds_write_b32 v88, v15 offset:3124
	ds_write_b32 v88, v16 offset:3128
	ds_write_b32 v88, v17 offset:3132
	v_mul_f32_e32 v18, v18, v71
	v_mul_f32_e32 v19, v19, v71
	v_mul_f32_e32 v20, v20, v71
	v_mul_f32_e32 v21, v21, v71
	ds_write_b32 v88, v18 offset:4160
	ds_write_b32 v88, v19 offset:4164
	ds_write_b32 v88, v20 offset:4168
	ds_write_b32 v88, v21 offset:4172
	v_mul_f32_e32 v22, v22, v72
	v_mul_f32_e32 v23, v23, v72
	v_mul_f32_e32 v24, v24, v72
	v_mul_f32_e32 v25, v25, v72
	ds_write_b32 v88, v22 offset:5200
	ds_write_b32 v88, v23 offset:5204
	ds_write_b32 v88, v24 offset:5208
	ds_write_b32 v88, v25 offset:5212
	v_mul_f32_e32 v26, v26, v73
	v_mul_f32_e32 v27, v27, v73
	v_mul_f32_e32 v28, v28, v73
	v_mul_f32_e32 v29, v29, v73
	ds_write_b32 v88, v26 offset:6240
	ds_write_b32 v88, v27 offset:6244
	ds_write_b32 v88, v28 offset:6248
	ds_write_b32 v88, v29 offset:6252
	v_mul_f32_e32 v30, v30, v74
	v_mul_f32_e32 v31, v31, v74
	v_mul_f32_e32 v32, v32, v74
	v_mul_f32_e32 v33, v33, v74
	ds_write_b32 v88, v30 offset:7280
	ds_write_b32 v88, v31 offset:7284
	ds_write_b32 v88, v32 offset:7288
	ds_write_b32 v88, v33 offset:7292
	v_mul_f32_e32 v34, v34, v75
	v_mul_f32_e32 v35, v35, v75
	v_mul_f32_e32 v36, v36, v75
	v_mul_f32_e32 v37, v37, v75
	ds_write_b32 v88, v34 offset:8320
	ds_write_b32 v88, v35 offset:8324
	ds_write_b32 v88, v36 offset:8328
	ds_write_b32 v88, v37 offset:8332
	v_mul_f32_e32 v38, v38, v76
	v_mul_f32_e32 v39, v39, v76
	v_mul_f32_e32 v40, v40, v76
	v_mul_f32_e32 v41, v41, v76
	ds_write_b32 v88, v38 offset:9360
	ds_write_b32 v88, v39 offset:9364
	ds_write_b32 v88, v40 offset:9368
	ds_write_b32 v88, v41 offset:9372
	v_mul_f32_e32 v42, v42, v77
	v_mul_f32_e32 v43, v43, v77
	v_mul_f32_e32 v44, v44, v77
	v_mul_f32_e32 v45, v45, v77
	ds_write_b32 v88, v42 offset:10400
	ds_write_b32 v88, v43 offset:10404
	ds_write_b32 v88, v44 offset:10408
	ds_write_b32 v88, v45 offset:10412
	v_mul_f32_e32 v46, v46, v78
	v_mul_f32_e32 v47, v47, v78
	v_mul_f32_e32 v48, v48, v78
	v_mul_f32_e32 v49, v49, v78
	ds_write_b32 v88, v46 offset:11440
	ds_write_b32 v88, v47 offset:11444
	ds_write_b32 v88, v48 offset:11448
	ds_write_b32 v88, v49 offset:11452
	v_mul_f32_e32 v50, v50, v79
	v_mul_f32_e32 v51, v51, v79
	v_mul_f32_e32 v52, v52, v79
	v_mul_f32_e32 v53, v53, v79
	ds_write_b32 v88, v50 offset:12480
	ds_write_b32 v88, v51 offset:12484
	ds_write_b32 v88, v52 offset:12488
	ds_write_b32 v88, v53 offset:12492
	v_mul_f32_e32 v54, v54, v80
	v_mul_f32_e32 v55, v55, v80
	v_mul_f32_e32 v56, v56, v80
	v_mul_f32_e32 v57, v57, v80
	ds_write_b32 v88, v54 offset:13520
	ds_write_b32 v88, v55 offset:13524
	ds_write_b32 v88, v56 offset:13528
	ds_write_b32 v88, v57 offset:13532
	v_mul_f32_e32 v58, v58, v81
	v_mul_f32_e32 v59, v59, v81
	v_mul_f32_e32 v60, v60, v81
	v_mul_f32_e32 v61, v61, v81
	ds_write_b32 v88, v58 offset:14560
	ds_write_b32 v88, v59 offset:14564
	ds_write_b32 v88, v60 offset:14568
	ds_write_b32 v88, v61 offset:14572
	v_mul_f32_e32 v62, v62, v82
	v_mul_f32_e32 v63, v63, v82
	v_mul_f32_e32 v64, v64, v82
	v_mul_f32_e32 v65, v65, v82
	ds_write_b32 v88, v62 offset:15600
	ds_write_b32 v88, v63 offset:15604
	ds_write_b32 v88, v64 offset:15608
	ds_write_b32 v88, v65 offset:15612
	ds_read_b32 v2, v89 offset:0
	ds_read_b32 v3, v89 offset:260
	ds_read_b32 v4, v89 offset:520
	ds_read_b32 v5, v89 offset:780
	ds_read_b32 v6, v89 offset:1040
	ds_read_b32 v7, v89 offset:1300
	ds_read_b32 v8, v89 offset:1560
	ds_read_b32 v9, v89 offset:1820
	ds_read_b32 v10, v89 offset:32
	ds_read_b32 v11, v89 offset:292
	ds_read_b32 v12, v89 offset:552
	ds_read_b32 v13, v89 offset:812
	ds_read_b32 v14, v89 offset:1072
	ds_read_b32 v15, v89 offset:1332
	ds_read_b32 v16, v89 offset:1592
	ds_read_b32 v17, v89 offset:1852
	ds_read_b32 v18, v89 offset:64
	ds_read_b32 v19, v89 offset:324
	ds_read_b32 v20, v89 offset:584
	ds_read_b32 v21, v89 offset:844
	ds_read_b32 v22, v89 offset:1104
	ds_read_b32 v23, v89 offset:1364
	ds_read_b32 v24, v89 offset:1624
	ds_read_b32 v25, v89 offset:1884
	ds_read_b32 v26, v89 offset:96
	ds_read_b32 v27, v89 offset:356
	ds_read_b32 v28, v89 offset:616
	ds_read_b32 v29, v89 offset:876
	ds_read_b32 v30, v89 offset:1136
	ds_read_b32 v31, v89 offset:1396
	ds_read_b32 v32, v89 offset:1656
	ds_read_b32 v33, v89 offset:1916
	ds_read_b32 v34, v89 offset:128
	ds_read_b32 v35, v89 offset:388
	ds_read_b32 v36, v89 offset:648
	ds_read_b32 v37, v89 offset:908
	ds_read_b32 v38, v89 offset:1168
	ds_read_b32 v39, v89 offset:1428
	ds_read_b32 v40, v89 offset:1688
	ds_read_b32 v41, v89 offset:1948
	ds_read_b32 v42, v89 offset:160
	ds_read_b32 v43, v89 offset:420
	ds_read_b32 v44, v89 offset:680
	ds_read_b32 v45, v89 offset:940
	ds_read_b32 v46, v89 offset:1200
	ds_read_b32 v47, v89 offset:1460
	ds_read_b32 v48, v89 offset:1720
	ds_read_b32 v49, v89 offset:1980
	ds_read_b32 v50, v89 offset:192
	ds_read_b32 v51, v89 offset:452
	ds_read_b32 v52, v89 offset:712
	ds_read_b32 v53, v89 offset:972
	ds_read_b32 v54, v89 offset:1232
	ds_read_b32 v55, v89 offset:1492
	ds_read_b32 v56, v89 offset:1752
	ds_read_b32 v57, v89 offset:2012
	ds_read_b32 v58, v89 offset:224
	ds_read_b32 v59, v89 offset:484
	ds_read_b32 v60, v89 offset:744
	ds_read_b32 v61, v89 offset:1004
	ds_read_b32 v62, v89 offset:1264
	ds_read_b32 v63, v89 offset:1524
	ds_read_b32 v64, v89 offset:1784
	ds_read_b32 v65, v89 offset:2044
	s_waitcnt lgkmcnt(0)
	s_mov_b64 s[42:43], s[64:65]
	s_lshl_b32 s46, s67, 3
	v_cvt_pk_bf16_f32 v2, v2, v3
	v_cvt_pk_bf16_f32 v3, v4, v5
	v_cvt_pk_bf16_f32 v4, v6, v7
	v_cvt_pk_bf16_f32 v5, v8, v9
	global_store_dwordx4 v84, v[2:5], s[42:43]
	s_add_u32 s42, s42, s46
	s_addc_u32 s43, s43, 0
	v_cvt_pk_bf16_f32 v10, v10, v11
	v_cvt_pk_bf16_f32 v11, v12, v13
	v_cvt_pk_bf16_f32 v12, v14, v15
	v_cvt_pk_bf16_f32 v13, v16, v17
	global_store_dwordx4 v84, v[10:13], s[42:43]
	s_add_u32 s42, s42, s46
	s_addc_u32 s43, s43, 0
	v_cvt_pk_bf16_f32 v18, v18, v19
	v_cvt_pk_bf16_f32 v19, v20, v21
	v_cvt_pk_bf16_f32 v20, v22, v23
	v_cvt_pk_bf16_f32 v21, v24, v25
	global_store_dwordx4 v84, v[18:21], s[42:43]
	s_add_u32 s42, s42, s46
	s_addc_u32 s43, s43, 0
	v_cvt_pk_bf16_f32 v26, v26, v27
	v_cvt_pk_bf16_f32 v27, v28, v29
	v_cvt_pk_bf16_f32 v28, v30, v31
	v_cvt_pk_bf16_f32 v29, v32, v33
	global_store_dwordx4 v84, v[26:29], s[42:43]
	s_add_u32 s42, s42, s46
	s_addc_u32 s43, s43, 0
	v_cvt_pk_bf16_f32 v34, v34, v35
	v_cvt_pk_bf16_f32 v35, v36, v37
	v_cvt_pk_bf16_f32 v36, v38, v39
	v_cvt_pk_bf16_f32 v37, v40, v41
	global_store_dwordx4 v84, v[34:37], s[42:43]
	s_add_u32 s42, s42, s46
	s_addc_u32 s43, s43, 0
	v_cvt_pk_bf16_f32 v42, v42, v43
	v_cvt_pk_bf16_f32 v43, v44, v45
	v_cvt_pk_bf16_f32 v44, v46, v47
	v_cvt_pk_bf16_f32 v45, v48, v49
	global_store_dwordx4 v84, v[42:45], s[42:43]
	s_add_u32 s42, s42, s46
	s_addc_u32 s43, s43, 0
	v_cvt_pk_bf16_f32 v50, v50, v51
	v_cvt_pk_bf16_f32 v51, v52, v53
	v_cvt_pk_bf16_f32 v52, v54, v55
	v_cvt_pk_bf16_f32 v53, v56, v57
	global_store_dwordx4 v84, v[50:53], s[42:43]
	s_add_u32 s42, s42, s46
	s_addc_u32 s43, s43, 0
	v_cvt_pk_bf16_f32 v58, v58, v59
	v_cvt_pk_bf16_f32 v59, v60, v61
	v_cvt_pk_bf16_f32 v60, v62, v63
	v_cvt_pk_bf16_f32 v61, v64, v65
	global_store_dwordx4 v84, v[58:61], s[42:43]
.Lp0_done:
.LBB0_76:
	s_cmpk_lt_i32 s70, 0x4000
	s_cselect_b64 s[4:5], -1, 0
	v_writelane_b32 v254, s4, 9
	s_cmpk_gt_i32 s70, 0x3fff
	s_nop 0
	v_writelane_b32 v254, s5, 10
	s_cbranch_scc1 .LBB0_81
	s_ashr_i32 s71, s70, 31
	s_lshl_b64 s[8:9], s[70:71], 7
	v_mov_b32_e32 v67, 0
	v_lshl_add_u64 v[2:3], s[8:9], 0, v[66:67]
	s_mov_b64 s[8:9], 0x1be00000
	v_lshl_add_u64 v[2:3], v[2:3], 0, s[8:9]
	v_readlane_b32 s8, v254, 7
	v_readlane_b32 s9, v254, 8
	s_mov_b32 s14, s8
	s_ashr_i32 s15, s8, 31
	s_lshl_b64 s[10:11], s[70:71], 12
	s_lshl_b64 s[8:9], s[14:15], 7
	v_lshl_or_b32 v4, v1, 3, s10
	v_mov_b32_e32 v5, s11
	s_lshl_b64 s[10:11], s[14:15], 12
	s_lshl_b64 s[12:13], s[70:71], 13
	s_waitcnt lgkmcnt(0)
	s_add_u32 s12, s20, s12
	v_xor_b32_e32 v8, 4, v66
	v_xor_b32_e32 v9, 8, v66
	v_xor_b32_e32 v10, 16, v66
	v_xor_b32_e32 v11, 32, v66
	v_xor_b32_e32 v12, 64, v66
	v_xor_b32_e32 v13, 0x80, v66
	v_lshlrev_b32_e32 v66, 4, v1
	s_addc_u32 s13, s21, s13
	v_lshl_add_u64 v[6:7], s[12:13], 0, v[66:67]
	s_mov_b64 s[12:13], 0x1c00
	v_lshl_add_u64 v[6:7], v[6:7], 0, s[12:13]
	s_mov_b32 s12, s14
	v_writelane_b32 v254, s12, 7
	v_cmp_gt_u32_e64 s[4:5], 32, v1
	v_cmp_eq_u32_e64 s[6:7], 0, v1
	v_writelane_b32 v254, s13, 8
	s_lshl_b64 s[12:13], s[14:15], 13
	s_mov_b32 s14, 0x17e00000
	s_mov_b32 s15, s70
	s_branch .LBB0_79
